# grid barrier: mid local arriver issues one extra un-waited L2 write-back
# speedup vs baseline: 1.0215x; 1.0026x over previous
.LBB0_41:
	s_or_b64 exec, exec, s[6:7]
	v_cvt_f32_u32_e32 v6, v4
	s_waitcnt vmcnt(0)
	v_readfirstlane_b32 s6, v5
	v_sub_u32_e32 v5, 0, v4
	v_rcp_iflag_f32_e32 v6, v6
	v_add_u32_e32 v7, s6, v2
	v_mul_f32_e32 v6, 0x4f7ffffe, v6
	v_cvt_u32_f32_e32 v6, v6
	v_mul_lo_u32 v2, v5, v6
	v_mul_hi_u32 v2, v6, v2
	v_add_u32_e32 v2, v6, v2
	v_mul_hi_u32 v2, v7, v2
	v_mul_lo_u32 v5, v2, v4
	v_sub_u32_e32 v5, v7, v5
	v_add_u32_e32 v6, 1, v2
	v_sub_u32_e32 v8, v5, v4
	v_cmp_ge_u32_e32 vcc, v5, v4
	s_nop 1
	v_cndmask_b32_e32 v2, v2, v6, vcc
	v_cndmask_b32_e32 v5, v5, v8, vcc
	v_add_u32_e32 v6, 1, v2
	v_cmp_ge_u32_e32 vcc, v5, v4
	v_add_u32_e32 v5, 1, v7
	s_nop 0
	v_cndmask_b32_e32 v2, v2, v6, vcc
	v_mul_lo_u32 v6, v4, v2
	v_add_u32_e32 v4, v6, v4
	v_cmp_ne_u32_e32 vcc, v5, v4
	s_and_saveexec_b64 s[6:7], vcc
	s_xor_b64 s[6:7], exec, s[6:7]
	s_cbranch_execz .LBB0_55
	v_sub_u32_e32 v8, v4, v6
	v_sub_u32_e32 v6, v7, v6
	v_lshrrev_b32_e32 v8, 1, v8
	v_cmp_eq_u32_e32 vcc, v6, v8
	s_cbranch_vccz .Lbar_nomidwb
	buffer_wbl2 sc1
.Lbar_nomidwb:
	v_readlane_b32 s12, v252, 62
	v_readlane_b32 s13, v252, 63
	s_waitcnt lgkmcnt(0)
	s_nop 3
	global_load_dword v1, v3, s[12:13] sc1
	s_waitcnt vmcnt(0)
	v_cmp_eq_u32_e32 vcc, v1, v2
	s_and_saveexec_b64 s[12:13], vcc
	s_cbranch_execz .LBB0_54
	s_mov_b32 s24, 1
	s_mov_b64 s[14:15], 0
	s_branch .LBB0_45
